# attention block epilogues (both modes): lane-pair exchange by DPP quad_perm instead of 64 serialized ds_bpermute, one exec toggle for the 64 stores
# speedup vs baseline: 1.0121x; 1.0042x over previous
.LBB0_383:
	s_add_u32 s2, s16, 0x4000
	s_addc_u32 s3, s17, 0
	s_add_i32 s4, s72, s42
	s_mov_b32 s5, m0
	s_mov_b32 m0, s4
	s_nop 0
	global_load_lds_dwordx4 v197, s[16:17]
	s_mov_b32 m0, s5
	s_add_i32 s4, s72, s43
	s_mov_b32 s5, m0
	s_mov_b32 m0, s4
	s_nop 0
	global_load_lds_dwordx4 v198, s[16:17]
	s_mov_b32 m0, s5
	s_add_i32 s4, s72, s97
	s_mov_b32 s5, m0
	s_mov_b32 m0, s4
	s_nop 0
	global_load_lds_dwordx4 v199, s[48:49]
	s_mov_b32 m0, s5
	s_add_i32 s4, s72, s91
	s_mov_b32 s5, m0
	s_mov_b32 m0, s4
	s_nop 0
	global_load_lds_dwordx4 v200, s[48:49]
	s_mov_b32 m0, s5
	s_add_i32 s4, s74, s42
	s_mov_b32 s5, m0
	s_mov_b32 m0, s4
	s_nop 0
	global_load_lds_dwordx4 v197, s[2:3]
	s_mov_b32 m0, s5
	s_add_i32 s4, s74, s43
	s_mov_b32 s5, m0
	s_mov_b32 m0, s4
	s_nop 0
	global_load_lds_dwordx4 v198, s[2:3]
	s_mov_b32 m0, s5
	v_cmp_gt_u32_e32 vcc, 32, v196
	s_and_saveexec_b64 s[4:5], vcc
	ds_write_b32 v204, v2
	s_or_b64 exec, exec, s[4:5]
	s_waitcnt lgkmcnt(0)
	ds_read_b128 v[18:21], v203
	ds_read_b128 v[22:25], v203 offset:32
	ds_read_b128 v[26:29], v203 offset:64
	ds_read_b128 v[30:33], v203 offset:96
	v_and_b32_e32 v8, 1, v195
	v_lshlrev_b32_e32 v14, 1, v201
	v_cmp_eq_u32_e64 s[2:3], 0, v8
	v_or_b32_e32 v8, s93, v202
	v_lshl_or_b32 v14, v8, 12, v14
	s_waitcnt lgkmcnt(0)
	v_rcp_f32_e32 v18, v18
	v_rcp_f32_e32 v19, v19
	v_rcp_f32_e32 v20, v20
	v_rcp_f32_e32 v21, v21
	v_rcp_f32_e32 v22, v22
	v_rcp_f32_e32 v23, v23
	v_rcp_f32_e32 v24, v24
	v_rcp_f32_e32 v25, v25
	v_rcp_f32_e32 v26, v26
	v_rcp_f32_e32 v27, v27
	v_rcp_f32_e32 v28, v28
	v_rcp_f32_e32 v29, v29
	v_rcp_f32_e32 v30, v30
	v_rcp_f32_e32 v31, v31
	v_rcp_f32_e32 v32, v32
	v_rcp_f32_e32 v33, v33
	v_mul_f32_e32 v34, v96, v18
	v_mul_f32_e32 v35, v112, v18
	v_mul_f32_e32 v36, v128, v18
	v_mul_f32_e32 v37, v144, v18
	v_mov_b32_dpp v4, v34 quad_perm:[1,0,3,2] row_mask:0xf bank_mask:0xf
	v_mov_b32_dpp v5, v35 quad_perm:[1,0,3,2] row_mask:0xf bank_mask:0xf
	v_mov_b32_dpp v6, v36 quad_perm:[1,0,3,2] row_mask:0xf bank_mask:0xf
	v_mov_b32_dpp v7, v37 quad_perm:[1,0,3,2] row_mask:0xf bank_mask:0xf
	v_cvt_pk_bf16_f32 v34, v34, v4
	v_cvt_pk_bf16_f32 v35, v35, v5
	v_cvt_pk_bf16_f32 v36, v36, v6
	v_cvt_pk_bf16_f32 v37, v37, v7
	v_mul_f32_e32 v38, v97, v19
	v_mul_f32_e32 v39, v113, v19
	v_mul_f32_e32 v40, v129, v19
	v_mul_f32_e32 v41, v145, v19
	v_mov_b32_dpp v4, v38 quad_perm:[1,0,3,2] row_mask:0xf bank_mask:0xf
	v_mov_b32_dpp v5, v39 quad_perm:[1,0,3,2] row_mask:0xf bank_mask:0xf
	v_mov_b32_dpp v6, v40 quad_perm:[1,0,3,2] row_mask:0xf bank_mask:0xf
	v_mov_b32_dpp v7, v41 quad_perm:[1,0,3,2] row_mask:0xf bank_mask:0xf
	v_cvt_pk_bf16_f32 v38, v38, v4
	v_cvt_pk_bf16_f32 v39, v39, v5
	v_cvt_pk_bf16_f32 v40, v40, v6
	v_cvt_pk_bf16_f32 v41, v41, v7
	v_mul_f32_e32 v42, v98, v20
	v_mul_f32_e32 v43, v114, v20
	v_mul_f32_e32 v44, v130, v20
	v_mul_f32_e32 v45, v146, v20
	v_mov_b32_dpp v4, v42 quad_perm:[1,0,3,2] row_mask:0xf bank_mask:0xf
	v_mov_b32_dpp v5, v43 quad_perm:[1,0,3,2] row_mask:0xf bank_mask:0xf
	v_mov_b32_dpp v6, v44 quad_perm:[1,0,3,2] row_mask:0xf bank_mask:0xf
	v_mov_b32_dpp v7, v45 quad_perm:[1,0,3,2] row_mask:0xf bank_mask:0xf
	v_cvt_pk_bf16_f32 v42, v42, v4
	v_cvt_pk_bf16_f32 v43, v43, v5
	v_cvt_pk_bf16_f32 v44, v44, v6
	v_cvt_pk_bf16_f32 v45, v45, v7
	v_mul_f32_e32 v46, v99, v21
	v_mul_f32_e32 v47, v115, v21
	v_mul_f32_e32 v48, v131, v21
	v_mul_f32_e32 v49, v147, v21
	v_mov_b32_dpp v4, v46 quad_perm:[1,0,3,2] row_mask:0xf bank_mask:0xf
	v_mov_b32_dpp v5, v47 quad_perm:[1,0,3,2] row_mask:0xf bank_mask:0xf
	v_mov_b32_dpp v6, v48 quad_perm:[1,0,3,2] row_mask:0xf bank_mask:0xf
	v_mov_b32_dpp v7, v49 quad_perm:[1,0,3,2] row_mask:0xf bank_mask:0xf
	v_cvt_pk_bf16_f32 v46, v46, v4
	v_cvt_pk_bf16_f32 v47, v47, v5
	v_cvt_pk_bf16_f32 v48, v48, v6
	v_cvt_pk_bf16_f32 v49, v49, v7
	v_mul_f32_e32 v50, v100, v22
	v_mul_f32_e32 v51, v116, v22
	v_mul_f32_e32 v52, v132, v22
	v_mul_f32_e32 v53, v148, v22
	v_mov_b32_dpp v4, v50 quad_perm:[1,0,3,2] row_mask:0xf bank_mask:0xf
	v_mov_b32_dpp v5, v51 quad_perm:[1,0,3,2] row_mask:0xf bank_mask:0xf
	v_mov_b32_dpp v6, v52 quad_perm:[1,0,3,2] row_mask:0xf bank_mask:0xf
	v_mov_b32_dpp v7, v53 quad_perm:[1,0,3,2] row_mask:0xf bank_mask:0xf
	v_cvt_pk_bf16_f32 v50, v50, v4
	v_cvt_pk_bf16_f32 v51, v51, v5
	v_cvt_pk_bf16_f32 v52, v52, v6
	v_cvt_pk_bf16_f32 v53, v53, v7
	v_mul_f32_e32 v54, v101, v23
	v_mul_f32_e32 v55, v117, v23
	v_mul_f32_e32 v56, v133, v23
	v_mul_f32_e32 v57, v149, v23
	v_mov_b32_dpp v4, v54 quad_perm:[1,0,3,2] row_mask:0xf bank_mask:0xf
	v_mov_b32_dpp v5, v55 quad_perm:[1,0,3,2] row_mask:0xf bank_mask:0xf
	v_mov_b32_dpp v6, v56 quad_perm:[1,0,3,2] row_mask:0xf bank_mask:0xf
	v_mov_b32_dpp v7, v57 quad_perm:[1,0,3,2] row_mask:0xf bank_mask:0xf
	v_cvt_pk_bf16_f32 v54, v54, v4
	v_cvt_pk_bf16_f32 v55, v55, v5
	v_cvt_pk_bf16_f32 v56, v56, v6
	v_cvt_pk_bf16_f32 v57, v57, v7
	v_mul_f32_e32 v58, v102, v24
	v_mul_f32_e32 v59, v118, v24
	v_mul_f32_e32 v60, v134, v24
	v_mul_f32_e32 v61, v150, v24
	v_mov_b32_dpp v4, v58 quad_perm:[1,0,3,2] row_mask:0xf bank_mask:0xf
	v_mov_b32_dpp v5, v59 quad_perm:[1,0,3,2] row_mask:0xf bank_mask:0xf
	v_mov_b32_dpp v6, v60 quad_perm:[1,0,3,2] row_mask:0xf bank_mask:0xf
	v_mov_b32_dpp v7, v61 quad_perm:[1,0,3,2] row_mask:0xf bank_mask:0xf
	v_cvt_pk_bf16_f32 v58, v58, v4
	v_cvt_pk_bf16_f32 v59, v59, v5
	v_cvt_pk_bf16_f32 v60, v60, v6
	v_cvt_pk_bf16_f32 v61, v61, v7
	v_mul_f32_e32 v62, v103, v25
	v_mul_f32_e32 v63, v119, v25
	v_mul_f32_e32 v64, v135, v25
	v_mul_f32_e32 v65, v151, v25
	v_mov_b32_dpp v4, v62 quad_perm:[1,0,3,2] row_mask:0xf bank_mask:0xf
	v_mov_b32_dpp v5, v63 quad_perm:[1,0,3,2] row_mask:0xf bank_mask:0xf
	v_mov_b32_dpp v6, v64 quad_perm:[1,0,3,2] row_mask:0xf bank_mask:0xf
	v_mov_b32_dpp v7, v65 quad_perm:[1,0,3,2] row_mask:0xf bank_mask:0xf
	v_cvt_pk_bf16_f32 v62, v62, v4
	v_cvt_pk_bf16_f32 v63, v63, v5
	v_cvt_pk_bf16_f32 v64, v64, v6
	v_cvt_pk_bf16_f32 v65, v65, v7
	v_mul_f32_e32 v66, v104, v26
	v_mul_f32_e32 v67, v120, v26
	v_mul_f32_e32 v68, v136, v26
	v_mul_f32_e32 v69, v152, v26
	v_mov_b32_dpp v4, v66 quad_perm:[1,0,3,2] row_mask:0xf bank_mask:0xf
	v_mov_b32_dpp v5, v67 quad_perm:[1,0,3,2] row_mask:0xf bank_mask:0xf
	v_mov_b32_dpp v6, v68 quad_perm:[1,0,3,2] row_mask:0xf bank_mask:0xf
	v_mov_b32_dpp v7, v69 quad_perm:[1,0,3,2] row_mask:0xf bank_mask:0xf
	v_cvt_pk_bf16_f32 v66, v66, v4
	v_cvt_pk_bf16_f32 v67, v67, v5
	v_cvt_pk_bf16_f32 v68, v68, v6
	v_cvt_pk_bf16_f32 v69, v69, v7
	v_mul_f32_e32 v70, v105, v27
	v_mul_f32_e32 v71, v121, v27
	v_mul_f32_e32 v72, v137, v27
	v_mul_f32_e32 v73, v153, v27
	v_mov_b32_dpp v4, v70 quad_perm:[1,0,3,2] row_mask:0xf bank_mask:0xf
	v_mov_b32_dpp v5, v71 quad_perm:[1,0,3,2] row_mask:0xf bank_mask:0xf
	v_mov_b32_dpp v6, v72 quad_perm:[1,0,3,2] row_mask:0xf bank_mask:0xf
	v_mov_b32_dpp v7, v73 quad_perm:[1,0,3,2] row_mask:0xf bank_mask:0xf
	v_cvt_pk_bf16_f32 v70, v70, v4
	v_cvt_pk_bf16_f32 v71, v71, v5
	v_cvt_pk_bf16_f32 v72, v72, v6
	v_cvt_pk_bf16_f32 v73, v73, v7
	v_mul_f32_e32 v74, v106, v28
	v_mul_f32_e32 v75, v122, v28
	v_mul_f32_e32 v76, v138, v28
	v_mul_f32_e32 v77, v154, v28
	v_mov_b32_dpp v4, v74 quad_perm:[1,0,3,2] row_mask:0xf bank_mask:0xf
	v_mov_b32_dpp v5, v75 quad_perm:[1,0,3,2] row_mask:0xf bank_mask:0xf
	v_mov_b32_dpp v6, v76 quad_perm:[1,0,3,2] row_mask:0xf bank_mask:0xf
	v_mov_b32_dpp v7, v77 quad_perm:[1,0,3,2] row_mask:0xf bank_mask:0xf
	v_cvt_pk_bf16_f32 v74, v74, v4
	v_cvt_pk_bf16_f32 v75, v75, v5
	v_cvt_pk_bf16_f32 v76, v76, v6
	v_cvt_pk_bf16_f32 v77, v77, v7
	v_mul_f32_e32 v78, v107, v29
	v_mul_f32_e32 v79, v123, v29
	v_mul_f32_e32 v206, v139, v29
	v_mul_f32_e32 v207, v155, v29
	v_mov_b32_dpp v4, v78 quad_perm:[1,0,3,2] row_mask:0xf bank_mask:0xf
	v_mov_b32_dpp v5, v79 quad_perm:[1,0,3,2] row_mask:0xf bank_mask:0xf
	v_mov_b32_dpp v6, v206 quad_perm:[1,0,3,2] row_mask:0xf bank_mask:0xf
	v_mov_b32_dpp v7, v207 quad_perm:[1,0,3,2] row_mask:0xf bank_mask:0xf
	v_cvt_pk_bf16_f32 v78, v78, v4
	v_cvt_pk_bf16_f32 v79, v79, v5
	v_cvt_pk_bf16_f32 v206, v206, v6
	v_cvt_pk_bf16_f32 v207, v207, v7
	v_mul_f32_e32 v208, v108, v30
	v_mul_f32_e32 v209, v124, v30
	v_mul_f32_e32 v210, v140, v30
	v_mul_f32_e32 v211, v156, v30
	v_mov_b32_dpp v4, v208 quad_perm:[1,0,3,2] row_mask:0xf bank_mask:0xf
	v_mov_b32_dpp v5, v209 quad_perm:[1,0,3,2] row_mask:0xf bank_mask:0xf
	v_mov_b32_dpp v6, v210 quad_perm:[1,0,3,2] row_mask:0xf bank_mask:0xf
	v_mov_b32_dpp v7, v211 quad_perm:[1,0,3,2] row_mask:0xf bank_mask:0xf
	v_cvt_pk_bf16_f32 v208, v208, v4
	v_cvt_pk_bf16_f32 v209, v209, v5
	v_cvt_pk_bf16_f32 v210, v210, v6
	v_cvt_pk_bf16_f32 v211, v211, v7
	v_mul_f32_e32 v212, v109, v31
	v_mul_f32_e32 v213, v125, v31
	v_mul_f32_e32 v214, v141, v31
	v_mul_f32_e32 v215, v157, v31
	v_mov_b32_dpp v4, v212 quad_perm:[1,0,3,2] row_mask:0xf bank_mask:0xf
	v_mov_b32_dpp v5, v213 quad_perm:[1,0,3,2] row_mask:0xf bank_mask:0xf
	v_mov_b32_dpp v6, v214 quad_perm:[1,0,3,2] row_mask:0xf bank_mask:0xf
	v_mov_b32_dpp v7, v215 quad_perm:[1,0,3,2] row_mask:0xf bank_mask:0xf
	v_cvt_pk_bf16_f32 v212, v212, v4
	v_cvt_pk_bf16_f32 v213, v213, v5
	v_cvt_pk_bf16_f32 v214, v214, v6
	v_cvt_pk_bf16_f32 v215, v215, v7
	v_mul_f32_e32 v216, v110, v32
	v_mul_f32_e32 v217, v126, v32
	v_mul_f32_e32 v218, v142, v32
	v_mul_f32_e32 v219, v158, v32
	v_mov_b32_dpp v4, v216 quad_perm:[1,0,3,2] row_mask:0xf bank_mask:0xf
	v_mov_b32_dpp v5, v217 quad_perm:[1,0,3,2] row_mask:0xf bank_mask:0xf
	v_mov_b32_dpp v6, v218 quad_perm:[1,0,3,2] row_mask:0xf bank_mask:0xf
	v_mov_b32_dpp v7, v219 quad_perm:[1,0,3,2] row_mask:0xf bank_mask:0xf
	v_cvt_pk_bf16_f32 v216, v216, v4
	v_cvt_pk_bf16_f32 v217, v217, v5
	v_cvt_pk_bf16_f32 v218, v218, v6
	v_cvt_pk_bf16_f32 v219, v219, v7
	v_mul_f32_e32 v220, v111, v33
	v_mul_f32_e32 v221, v127, v33
	v_mul_f32_e32 v222, v143, v33
	v_mul_f32_e32 v223, v159, v33
	v_mov_b32_dpp v4, v220 quad_perm:[1,0,3,2] row_mask:0xf bank_mask:0xf
	v_mov_b32_dpp v5, v221 quad_perm:[1,0,3,2] row_mask:0xf bank_mask:0xf
	v_mov_b32_dpp v6, v222 quad_perm:[1,0,3,2] row_mask:0xf bank_mask:0xf
	v_mov_b32_dpp v7, v223 quad_perm:[1,0,3,2] row_mask:0xf bank_mask:0xf
	v_cvt_pk_bf16_f32 v220, v220, v4
	v_cvt_pk_bf16_f32 v221, v221, v5
	v_cvt_pk_bf16_f32 v222, v222, v6
	v_cvt_pk_bf16_f32 v223, v223, v7
	s_and_saveexec_b64 s[4:5], s[2:3]
	global_store_dword v14, v34, s[8:9]
	global_store_dword v14, v35, s[8:9] offset:64
	global_store_dword v14, v36, s[8:9] offset:128
	global_store_dword v14, v37, s[8:9] offset:192
	v_add_u32_e32 v11, 0x1000, v14
	global_store_dword v11, v38, s[8:9]
	global_store_dword v11, v39, s[8:9] offset:64
	global_store_dword v11, v40, s[8:9] offset:128
	global_store_dword v11, v41, s[8:9] offset:192
	v_add_u32_e32 v12, 0x2000, v14
	global_store_dword v12, v42, s[8:9]
	global_store_dword v12, v43, s[8:9] offset:64
	global_store_dword v12, v44, s[8:9] offset:128
	global_store_dword v12, v45, s[8:9] offset:192
	v_add_u32_e32 v13, 0x3000, v14
	global_store_dword v13, v46, s[8:9]
	global_store_dword v13, v47, s[8:9] offset:64
	global_store_dword v13, v48, s[8:9] offset:128
	global_store_dword v13, v49, s[8:9] offset:192
	v_add_u32_e32 v10, 0x8000, v14
	global_store_dword v10, v50, s[8:9]
	global_store_dword v10, v51, s[8:9] offset:64
	global_store_dword v10, v52, s[8:9] offset:128
	global_store_dword v10, v53, s[8:9] offset:192
	v_add_u32_e32 v11, 0x9000, v14
	global_store_dword v11, v54, s[8:9]
	global_store_dword v11, v55, s[8:9] offset:64
	global_store_dword v11, v56, s[8:9] offset:128
	global_store_dword v11, v57, s[8:9] offset:192
	v_add_u32_e32 v12, 0xa000, v14
	global_store_dword v12, v58, s[8:9]
	global_store_dword v12, v59, s[8:9] offset:64
	global_store_dword v12, v60, s[8:9] offset:128
	global_store_dword v12, v61, s[8:9] offset:192
	v_add_u32_e32 v13, 0xb000, v14
	global_store_dword v13, v62, s[8:9]
	global_store_dword v13, v63, s[8:9] offset:64
	global_store_dword v13, v64, s[8:9] offset:128
	global_store_dword v13, v65, s[8:9] offset:192
	v_add_u32_e32 v10, 0x10000, v14
	global_store_dword v10, v66, s[8:9]
	global_store_dword v10, v67, s[8:9] offset:64
	global_store_dword v10, v68, s[8:9] offset:128
	global_store_dword v10, v69, s[8:9] offset:192
	v_add_u32_e32 v11, 0x11000, v14
	global_store_dword v11, v70, s[8:9]
	global_store_dword v11, v71, s[8:9] offset:64
	global_store_dword v11, v72, s[8:9] offset:128
	global_store_dword v11, v73, s[8:9] offset:192
	v_add_u32_e32 v12, 0x12000, v14
	global_store_dword v12, v74, s[8:9]
	global_store_dword v12, v75, s[8:9] offset:64
	global_store_dword v12, v76, s[8:9] offset:128
	global_store_dword v12, v77, s[8:9] offset:192
	v_add_u32_e32 v13, 0x13000, v14
	global_store_dword v13, v78, s[8:9]
	global_store_dword v13, v79, s[8:9] offset:64
	global_store_dword v13, v206, s[8:9] offset:128
	global_store_dword v13, v207, s[8:9] offset:192
	v_add_u32_e32 v10, 0x18000, v14
	global_store_dword v10, v208, s[8:9]
	global_store_dword v10, v209, s[8:9] offset:64
	global_store_dword v10, v210, s[8:9] offset:128
	global_store_dword v10, v211, s[8:9] offset:192
	v_add_u32_e32 v11, 0x19000, v14
	global_store_dword v11, v212, s[8:9]
	global_store_dword v11, v213, s[8:9] offset:64
	global_store_dword v11, v214, s[8:9] offset:128
	global_store_dword v11, v215, s[8:9] offset:192
	v_add_u32_e32 v12, 0x1a000, v14
	global_store_dword v12, v216, s[8:9]
	global_store_dword v12, v217, s[8:9] offset:64
	global_store_dword v12, v218, s[8:9] offset:128
	global_store_dword v12, v219, s[8:9] offset:192
	v_add_u32_e32 v13, 0x1b000, v14
	global_store_dword v13, v220, s[8:9]
	global_store_dword v13, v221, s[8:9] offset:64
	global_store_dword v13, v222, s[8:9] offset:128
	global_store_dword v13, v223, s[8:9] offset:192
	s_branch .LBB0_287

.LBB0_1227:
	s_lshr_b32 s0, s11, 6
	s_or_b32 s12, s0, 3
	s_or_b32 s0, s0, 2
	s_lshl_b64 s[6:7], s[12:13], 14
	s_add_u32 s8, s44, s6
	s_mov_b32 s1, s13
	s_addc_u32 s9, s45, s7
	s_lshl_b64 s[54:55], s[0:1], 14
	s_add_u32 s54, s44, s54
	s_addc_u32 s55, s45, s55
	s_add_u32 s6, s46, s6
	s_addc_u32 s7, s47, s7
	s_add_i32 s52, s65, s90
	s_mov_b32 s56, m0
	s_mov_b32 m0, s52
	s_nop 0
	global_load_lds_dwordx4 v183, s[8:9]
	s_mov_b32 m0, s56
	s_add_i32 s52, s65, s2
	s_mov_b32 s56, m0
	s_mov_b32 m0, s52
	s_nop 0
	global_load_lds_dwordx4 v184, s[8:9]
	s_mov_b32 m0, s56
	s_lshl_b64 s[8:9], s[12:13], 8
	s_add_u32 s8, s48, s8
	s_addc_u32 s9, s49, s9
	s_ashr_i32 s12, s65, 6
	s_cmp_lg_u32 0, -1
	s_cselect_b32 s52, 0, 0
	s_add_i32 s52, s52, 0x18800
	s_add_i32 s12, s12, s52
	s_mov_b32 s56, m0
	s_mov_b32 m0, s12
	s_nop 0
	global_load_lds_dword v185, s[8:9]
	s_mov_b32 m0, s56
	s_add_i32 s8, s65, s83
	s_mov_b32 s9, m0
	s_mov_b32 m0, s8
	s_nop 0
	global_load_lds_dwordx4 v187, s[6:7]
	s_mov_b32 m0, s9
	s_add_i32 s8, s65, s3
	s_mov_b32 s9, m0
	s_mov_b32 m0, s8
	s_nop 0
	global_load_lds_dwordx4 v186, s[6:7]
	s_mov_b32 m0, s9
	s_add_i32 s6, s53, s90
	s_mov_b32 s7, m0
	s_mov_b32 m0, s6
	s_nop 0
	global_load_lds_dwordx4 v183, s[54:55]
	s_mov_b32 m0, s7
	s_add_i32 s6, s53, s2
	s_lshl_b64 s[0:1], s[0:1], 8
	s_add_u32 s0, s48, s0
	s_mov_b32 s7, m0
	s_mov_b32 m0, s6
	s_nop 0
	global_load_lds_dwordx4 v184, s[54:55]
	s_mov_b32 m0, s7
	s_addc_u32 s1, s49, s1
	s_ashr_i32 s6, s53, 6
	s_add_i32 s6, s6, s52
	s_mov_b32 s7, m0
	s_mov_b32 m0, s6
	s_nop 0
	global_load_lds_dword v185, s[0:1]
	s_mov_b32 m0, s7
	v_cmp_gt_u32_e32 vcc, 32, v182
	s_and_saveexec_b64 s[0:1], vcc
	ds_write_b32 v191, v1
	s_or_b64 exec, exec, s[0:1]
	s_waitcnt lgkmcnt(0)
	ds_read_b128 v[18:21], v190
	ds_read_b128 v[22:25], v190 offset:32
	ds_read_b128 v[26:29], v190 offset:64
	ds_read_b128 v[30:33], v190 offset:96
	v_and_b32_e32 v8, 1, v181
	v_lshlrev_b32_e32 v14, 1, v188
	v_cmp_eq_u32_e64 s[6:7], 0, v8
	v_or_b32_e32 v8, s93, v189
	v_lshl_or_b32 v14, v8, 12, v14
	s_waitcnt lgkmcnt(0)
	v_rcp_f32_e32 v18, v18
	v_rcp_f32_e32 v19, v19
	v_rcp_f32_e32 v20, v20
	v_rcp_f32_e32 v21, v21
	v_rcp_f32_e32 v22, v22
	v_rcp_f32_e32 v23, v23
	v_rcp_f32_e32 v24, v24
	v_rcp_f32_e32 v25, v25
	v_rcp_f32_e32 v26, v26
	v_rcp_f32_e32 v27, v27
	v_rcp_f32_e32 v28, v28
	v_rcp_f32_e32 v29, v29
	v_rcp_f32_e32 v30, v30
	v_rcp_f32_e32 v31, v31
	v_rcp_f32_e32 v32, v32
	v_rcp_f32_e32 v33, v33
	v_mul_f32_e32 v34, v80, v18
	v_mul_f32_e32 v35, v96, v18
	v_mul_f32_e32 v36, v112, v18
	v_mul_f32_e32 v37, v128, v18
	v_mov_b32_dpp v4, v34 quad_perm:[1,0,3,2] row_mask:0xf bank_mask:0xf
	v_mov_b32_dpp v5, v35 quad_perm:[1,0,3,2] row_mask:0xf bank_mask:0xf
	v_mov_b32_dpp v6, v36 quad_perm:[1,0,3,2] row_mask:0xf bank_mask:0xf
	v_mov_b32_dpp v7, v37 quad_perm:[1,0,3,2] row_mask:0xf bank_mask:0xf
	v_cvt_pk_bf16_f32 v34, v34, v4
	v_cvt_pk_bf16_f32 v35, v35, v5
	v_cvt_pk_bf16_f32 v36, v36, v6
	v_cvt_pk_bf16_f32 v37, v37, v7
	v_mul_f32_e32 v38, v81, v19
	v_mul_f32_e32 v39, v97, v19
	v_mul_f32_e32 v40, v113, v19
	v_mul_f32_e32 v41, v129, v19
	v_mov_b32_dpp v4, v38 quad_perm:[1,0,3,2] row_mask:0xf bank_mask:0xf
	v_mov_b32_dpp v5, v39 quad_perm:[1,0,3,2] row_mask:0xf bank_mask:0xf
	v_mov_b32_dpp v6, v40 quad_perm:[1,0,3,2] row_mask:0xf bank_mask:0xf
	v_mov_b32_dpp v7, v41 quad_perm:[1,0,3,2] row_mask:0xf bank_mask:0xf
	v_cvt_pk_bf16_f32 v38, v38, v4
	v_cvt_pk_bf16_f32 v39, v39, v5
	v_cvt_pk_bf16_f32 v40, v40, v6
	v_cvt_pk_bf16_f32 v41, v41, v7
	v_mul_f32_e32 v42, v82, v20
	v_mul_f32_e32 v43, v98, v20
	v_mul_f32_e32 v44, v114, v20
	v_mul_f32_e32 v45, v130, v20
	v_mov_b32_dpp v4, v42 quad_perm:[1,0,3,2] row_mask:0xf bank_mask:0xf
	v_mov_b32_dpp v5, v43 quad_perm:[1,0,3,2] row_mask:0xf bank_mask:0xf
	v_mov_b32_dpp v6, v44 quad_perm:[1,0,3,2] row_mask:0xf bank_mask:0xf
	v_mov_b32_dpp v7, v45 quad_perm:[1,0,3,2] row_mask:0xf bank_mask:0xf
	v_cvt_pk_bf16_f32 v42, v42, v4
	v_cvt_pk_bf16_f32 v43, v43, v5
	v_cvt_pk_bf16_f32 v44, v44, v6
	v_cvt_pk_bf16_f32 v45, v45, v7
	v_mul_f32_e32 v46, v83, v21
	v_mul_f32_e32 v47, v99, v21
	v_mul_f32_e32 v48, v115, v21
	v_mul_f32_e32 v49, v131, v21
	v_mov_b32_dpp v4, v46 quad_perm:[1,0,3,2] row_mask:0xf bank_mask:0xf
	v_mov_b32_dpp v5, v47 quad_perm:[1,0,3,2] row_mask:0xf bank_mask:0xf
	v_mov_b32_dpp v6, v48 quad_perm:[1,0,3,2] row_mask:0xf bank_mask:0xf
	v_mov_b32_dpp v7, v49 quad_perm:[1,0,3,2] row_mask:0xf bank_mask:0xf
	v_cvt_pk_bf16_f32 v46, v46, v4
	v_cvt_pk_bf16_f32 v47, v47, v5
	v_cvt_pk_bf16_f32 v48, v48, v6
	v_cvt_pk_bf16_f32 v49, v49, v7
	v_mul_f32_e32 v50, v84, v22
	v_mul_f32_e32 v51, v100, v22
	v_mul_f32_e32 v52, v116, v22
	v_mul_f32_e32 v53, v132, v22
	v_mov_b32_dpp v4, v50 quad_perm:[1,0,3,2] row_mask:0xf bank_mask:0xf
	v_mov_b32_dpp v5, v51 quad_perm:[1,0,3,2] row_mask:0xf bank_mask:0xf
	v_mov_b32_dpp v6, v52 quad_perm:[1,0,3,2] row_mask:0xf bank_mask:0xf
	v_mov_b32_dpp v7, v53 quad_perm:[1,0,3,2] row_mask:0xf bank_mask:0xf
	v_cvt_pk_bf16_f32 v50, v50, v4
	v_cvt_pk_bf16_f32 v51, v51, v5
	v_cvt_pk_bf16_f32 v52, v52, v6
	v_cvt_pk_bf16_f32 v53, v53, v7
	v_mul_f32_e32 v54, v85, v23
	v_mul_f32_e32 v55, v101, v23
	v_mul_f32_e32 v56, v117, v23
	v_mul_f32_e32 v57, v133, v23
	v_mov_b32_dpp v4, v54 quad_perm:[1,0,3,2] row_mask:0xf bank_mask:0xf
	v_mov_b32_dpp v5, v55 quad_perm:[1,0,3,2] row_mask:0xf bank_mask:0xf
	v_mov_b32_dpp v6, v56 quad_perm:[1,0,3,2] row_mask:0xf bank_mask:0xf
	v_mov_b32_dpp v7, v57 quad_perm:[1,0,3,2] row_mask:0xf bank_mask:0xf
	v_cvt_pk_bf16_f32 v54, v54, v4
	v_cvt_pk_bf16_f32 v55, v55, v5
	v_cvt_pk_bf16_f32 v56, v56, v6
	v_cvt_pk_bf16_f32 v57, v57, v7
	v_mul_f32_e32 v58, v86, v24
	v_mul_f32_e32 v59, v102, v24
	v_mul_f32_e32 v60, v118, v24
	v_mul_f32_e32 v61, v134, v24
	v_mov_b32_dpp v4, v58 quad_perm:[1,0,3,2] row_mask:0xf bank_mask:0xf
	v_mov_b32_dpp v5, v59 quad_perm:[1,0,3,2] row_mask:0xf bank_mask:0xf
	v_mov_b32_dpp v6, v60 quad_perm:[1,0,3,2] row_mask:0xf bank_mask:0xf
	v_mov_b32_dpp v7, v61 quad_perm:[1,0,3,2] row_mask:0xf bank_mask:0xf
	v_cvt_pk_bf16_f32 v58, v58, v4
	v_cvt_pk_bf16_f32 v59, v59, v5
	v_cvt_pk_bf16_f32 v60, v60, v6
	v_cvt_pk_bf16_f32 v61, v61, v7
	v_mul_f32_e32 v62, v87, v25
	v_mul_f32_e32 v63, v103, v25
	v_mul_f32_e32 v64, v119, v25
	v_mul_f32_e32 v65, v135, v25
	v_mov_b32_dpp v4, v62 quad_perm:[1,0,3,2] row_mask:0xf bank_mask:0xf
	v_mov_b32_dpp v5, v63 quad_perm:[1,0,3,2] row_mask:0xf bank_mask:0xf
	v_mov_b32_dpp v6, v64 quad_perm:[1,0,3,2] row_mask:0xf bank_mask:0xf
	v_mov_b32_dpp v7, v65 quad_perm:[1,0,3,2] row_mask:0xf bank_mask:0xf
	v_cvt_pk_bf16_f32 v62, v62, v4
	v_cvt_pk_bf16_f32 v63, v63, v5
	v_cvt_pk_bf16_f32 v64, v64, v6
	v_cvt_pk_bf16_f32 v65, v65, v7
	v_mul_f32_e32 v66, v88, v26
	v_mul_f32_e32 v67, v104, v26
	v_mul_f32_e32 v68, v120, v26
	v_mul_f32_e32 v69, v136, v26
	v_mov_b32_dpp v4, v66 quad_perm:[1,0,3,2] row_mask:0xf bank_mask:0xf
	v_mov_b32_dpp v5, v67 quad_perm:[1,0,3,2] row_mask:0xf bank_mask:0xf
	v_mov_b32_dpp v6, v68 quad_perm:[1,0,3,2] row_mask:0xf bank_mask:0xf
	v_mov_b32_dpp v7, v69 quad_perm:[1,0,3,2] row_mask:0xf bank_mask:0xf
	v_cvt_pk_bf16_f32 v66, v66, v4
	v_cvt_pk_bf16_f32 v67, v67, v5
	v_cvt_pk_bf16_f32 v68, v68, v6
	v_cvt_pk_bf16_f32 v69, v69, v7
	v_mul_f32_e32 v70, v89, v27
	v_mul_f32_e32 v71, v105, v27
	v_mul_f32_e32 v72, v121, v27
	v_mul_f32_e32 v73, v137, v27
	v_mov_b32_dpp v4, v70 quad_perm:[1,0,3,2] row_mask:0xf bank_mask:0xf
	v_mov_b32_dpp v5, v71 quad_perm:[1,0,3,2] row_mask:0xf bank_mask:0xf
	v_mov_b32_dpp v6, v72 quad_perm:[1,0,3,2] row_mask:0xf bank_mask:0xf
	v_mov_b32_dpp v7, v73 quad_perm:[1,0,3,2] row_mask:0xf bank_mask:0xf
	v_cvt_pk_bf16_f32 v70, v70, v4
	v_cvt_pk_bf16_f32 v71, v71, v5
	v_cvt_pk_bf16_f32 v72, v72, v6
	v_cvt_pk_bf16_f32 v73, v73, v7
	v_mul_f32_e32 v74, v90, v28
	v_mul_f32_e32 v75, v106, v28
	v_mul_f32_e32 v76, v122, v28
	v_mul_f32_e32 v77, v138, v28
	v_mov_b32_dpp v4, v74 quad_perm:[1,0,3,2] row_mask:0xf bank_mask:0xf
	v_mov_b32_dpp v5, v75 quad_perm:[1,0,3,2] row_mask:0xf bank_mask:0xf
	v_mov_b32_dpp v6, v76 quad_perm:[1,0,3,2] row_mask:0xf bank_mask:0xf
	v_mov_b32_dpp v7, v77 quad_perm:[1,0,3,2] row_mask:0xf bank_mask:0xf
	v_cvt_pk_bf16_f32 v74, v74, v4
	v_cvt_pk_bf16_f32 v75, v75, v5
	v_cvt_pk_bf16_f32 v76, v76, v6
	v_cvt_pk_bf16_f32 v77, v77, v7
	v_mul_f32_e32 v78, v91, v29
	v_mul_f32_e32 v79, v107, v29
	v_mul_f32_e32 v206, v123, v29
	v_mul_f32_e32 v207, v139, v29
	v_mov_b32_dpp v4, v78 quad_perm:[1,0,3,2] row_mask:0xf bank_mask:0xf
	v_mov_b32_dpp v5, v79 quad_perm:[1,0,3,2] row_mask:0xf bank_mask:0xf
	v_mov_b32_dpp v6, v206 quad_perm:[1,0,3,2] row_mask:0xf bank_mask:0xf
	v_mov_b32_dpp v7, v207 quad_perm:[1,0,3,2] row_mask:0xf bank_mask:0xf
	v_cvt_pk_bf16_f32 v78, v78, v4
	v_cvt_pk_bf16_f32 v79, v79, v5
	v_cvt_pk_bf16_f32 v206, v206, v6
	v_cvt_pk_bf16_f32 v207, v207, v7
	v_mul_f32_e32 v208, v92, v30
	v_mul_f32_e32 v209, v108, v30
	v_mul_f32_e32 v210, v124, v30
	v_mul_f32_e32 v211, v140, v30
	v_mov_b32_dpp v4, v208 quad_perm:[1,0,3,2] row_mask:0xf bank_mask:0xf
	v_mov_b32_dpp v5, v209 quad_perm:[1,0,3,2] row_mask:0xf bank_mask:0xf
	v_mov_b32_dpp v6, v210 quad_perm:[1,0,3,2] row_mask:0xf bank_mask:0xf
	v_mov_b32_dpp v7, v211 quad_perm:[1,0,3,2] row_mask:0xf bank_mask:0xf
	v_cvt_pk_bf16_f32 v208, v208, v4
	v_cvt_pk_bf16_f32 v209, v209, v5
	v_cvt_pk_bf16_f32 v210, v210, v6
	v_cvt_pk_bf16_f32 v211, v211, v7
	v_mul_f32_e32 v212, v93, v31
	v_mul_f32_e32 v213, v109, v31
	v_mul_f32_e32 v214, v125, v31
	v_mul_f32_e32 v215, v141, v31
	v_mov_b32_dpp v4, v212 quad_perm:[1,0,3,2] row_mask:0xf bank_mask:0xf
	v_mov_b32_dpp v5, v213 quad_perm:[1,0,3,2] row_mask:0xf bank_mask:0xf
	v_mov_b32_dpp v6, v214 quad_perm:[1,0,3,2] row_mask:0xf bank_mask:0xf
	v_mov_b32_dpp v7, v215 quad_perm:[1,0,3,2] row_mask:0xf bank_mask:0xf
	v_cvt_pk_bf16_f32 v212, v212, v4
	v_cvt_pk_bf16_f32 v213, v213, v5
	v_cvt_pk_bf16_f32 v214, v214, v6
	v_cvt_pk_bf16_f32 v215, v215, v7
	v_mul_f32_e32 v216, v94, v32
	v_mul_f32_e32 v217, v110, v32
	v_mul_f32_e32 v218, v126, v32
	v_mul_f32_e32 v219, v142, v32
	v_mov_b32_dpp v4, v216 quad_perm:[1,0,3,2] row_mask:0xf bank_mask:0xf
	v_mov_b32_dpp v5, v217 quad_perm:[1,0,3,2] row_mask:0xf bank_mask:0xf
	v_mov_b32_dpp v6, v218 quad_perm:[1,0,3,2] row_mask:0xf bank_mask:0xf
	v_mov_b32_dpp v7, v219 quad_perm:[1,0,3,2] row_mask:0xf bank_mask:0xf
	v_cvt_pk_bf16_f32 v216, v216, v4
	v_cvt_pk_bf16_f32 v217, v217, v5
	v_cvt_pk_bf16_f32 v218, v218, v6
	v_cvt_pk_bf16_f32 v219, v219, v7
	v_mul_f32_e32 v220, v95, v33
	v_mul_f32_e32 v221, v111, v33
	v_mul_f32_e32 v222, v127, v33
	v_mul_f32_e32 v223, v143, v33
	v_mov_b32_dpp v4, v220 quad_perm:[1,0,3,2] row_mask:0xf bank_mask:0xf
	v_mov_b32_dpp v5, v221 quad_perm:[1,0,3,2] row_mask:0xf bank_mask:0xf
	v_mov_b32_dpp v6, v222 quad_perm:[1,0,3,2] row_mask:0xf bank_mask:0xf
	v_mov_b32_dpp v7, v223 quad_perm:[1,0,3,2] row_mask:0xf bank_mask:0xf
	v_cvt_pk_bf16_f32 v220, v220, v4
	v_cvt_pk_bf16_f32 v221, v221, v5
	v_cvt_pk_bf16_f32 v222, v222, v6
	v_cvt_pk_bf16_f32 v223, v223, v7
	s_and_saveexec_b64 s[0:1], s[6:7]
	global_store_dword v14, v34, s[14:15]
	global_store_dword v14, v35, s[14:15] offset:64
	global_store_dword v14, v36, s[14:15] offset:128
	global_store_dword v14, v37, s[14:15] offset:192
	v_add_u32_e32 v11, 0x1000, v14
	global_store_dword v11, v38, s[14:15]
	global_store_dword v11, v39, s[14:15] offset:64
	global_store_dword v11, v40, s[14:15] offset:128
	global_store_dword v11, v41, s[14:15] offset:192
	v_add_u32_e32 v12, 0x2000, v14
	global_store_dword v12, v42, s[14:15]
	global_store_dword v12, v43, s[14:15] offset:64
	global_store_dword v12, v44, s[14:15] offset:128
	global_store_dword v12, v45, s[14:15] offset:192
	v_add_u32_e32 v13, 0x3000, v14
	global_store_dword v13, v46, s[14:15]
	global_store_dword v13, v47, s[14:15] offset:64
	global_store_dword v13, v48, s[14:15] offset:128
	global_store_dword v13, v49, s[14:15] offset:192
	v_add_u32_e32 v10, 0x8000, v14
	global_store_dword v10, v50, s[14:15]
	global_store_dword v10, v51, s[14:15] offset:64
	global_store_dword v10, v52, s[14:15] offset:128
	global_store_dword v10, v53, s[14:15] offset:192
	v_add_u32_e32 v11, 0x9000, v14
	global_store_dword v11, v54, s[14:15]
	global_store_dword v11, v55, s[14:15] offset:64
	global_store_dword v11, v56, s[14:15] offset:128
	global_store_dword v11, v57, s[14:15] offset:192
	v_add_u32_e32 v12, 0xa000, v14
	global_store_dword v12, v58, s[14:15]
	global_store_dword v12, v59, s[14:15] offset:64
	global_store_dword v12, v60, s[14:15] offset:128
	global_store_dword v12, v61, s[14:15] offset:192
	v_add_u32_e32 v13, 0xb000, v14
	global_store_dword v13, v62, s[14:15]
	global_store_dword v13, v63, s[14:15] offset:64
	global_store_dword v13, v64, s[14:15] offset:128
	global_store_dword v13, v65, s[14:15] offset:192
	v_add_u32_e32 v10, 0x10000, v14
	global_store_dword v10, v66, s[14:15]
	global_store_dword v10, v67, s[14:15] offset:64
	global_store_dword v10, v68, s[14:15] offset:128
	global_store_dword v10, v69, s[14:15] offset:192
	v_add_u32_e32 v11, 0x11000, v14
	global_store_dword v11, v70, s[14:15]
	global_store_dword v11, v71, s[14:15] offset:64
	global_store_dword v11, v72, s[14:15] offset:128
	global_store_dword v11, v73, s[14:15] offset:192
	v_add_u32_e32 v12, 0x12000, v14
	global_store_dword v12, v74, s[14:15]
	global_store_dword v12, v75, s[14:15] offset:64
	global_store_dword v12, v76, s[14:15] offset:128
	global_store_dword v12, v77, s[14:15] offset:192
	v_add_u32_e32 v13, 0x13000, v14
	global_store_dword v13, v78, s[14:15]
	global_store_dword v13, v79, s[14:15] offset:64
	global_store_dword v13, v206, s[14:15] offset:128
	global_store_dword v13, v207, s[14:15] offset:192
	v_add_u32_e32 v10, 0x18000, v14
	global_store_dword v10, v208, s[14:15]
	global_store_dword v10, v209, s[14:15] offset:64
	global_store_dword v10, v210, s[14:15] offset:128
	global_store_dword v10, v211, s[14:15] offset:192
	v_add_u32_e32 v11, 0x19000, v14
	global_store_dword v11, v212, s[14:15]
	global_store_dword v11, v213, s[14:15] offset:64
	global_store_dword v11, v214, s[14:15] offset:128
	global_store_dword v11, v215, s[14:15] offset:192
	v_add_u32_e32 v12, 0x1a000, v14
	global_store_dword v12, v216, s[14:15]
	global_store_dword v12, v217, s[14:15] offset:64
	global_store_dword v12, v218, s[14:15] offset:128
	global_store_dword v12, v219, s[14:15] offset:192
	v_add_u32_e32 v13, 0x1b000, v14
	global_store_dword v13, v220, s[14:15]
	global_store_dword v13, v221, s[14:15] offset:64
	global_store_dword v13, v222, s[14:15] offset:128
	global_store_dword v13, v223, s[14:15] offset:192
	s_branch .LBB0_1139
